# stack on v93: dil Q prefetch one item ahead + tok0_mix_dil tail batched + exact mem_attn max-chain trim; hot-loop placement preserved
# speedup vs baseline: 1.0142x; 1.0034x over previous
; __global__ void __launch_bounds__(NTHREADS, 2) megak(Params p) {
;     ...
;                 if (gridDim.x == 256) {
;                     const int grp = blockIdx.x >> 3;
;                     for (int j = 0; j < 2; ++j) mem_attn_item(lds, PJ, DIL_N, DB_QM, DB_GATE, kvl, BR, st.b0, ((blockIdx.x & 7) * 2 + j) + 16 * grp, tid, wid, lane, j == 0);
;                 } else
;                 for (int it = blockIdx.x; it < SLAB_B * 64; it += gridDim.x) mem_attn_item(lds, PJ, DIL_N, DB_QM, DB_GATE, kvl, BR, st.b0, it, tid, wid, lane);
.LBB0_447:
	s_nop 0
	s_nop 0
	s_nop 0
	s_nop 0
	s_nop 0
	s_nop 0
	s_nop 0
	s_nop 0
	s_nop 0
	s_nop 0
	s_nop 0
	s_nop 0
	s_nop 0
	s_nop 0
	s_mov_b64 s[22:23], 0

; DI void tok0_gemv(ldsp lds, const float* src, size_t sstride, const float* nw, const float* W, int N, float* Y, int ldy, const float* resid, size_t rstride, int task, int tid, int wid, int lane) {
;     ...
;     {
;         float4 v[4][4];
; #pragma unroll
;         for (int q = 0; q < 4; ++q) { const float* xr = src + (size_t)(wid + 8 * q) * sstride;
; #pragma unroll
;             for (int i = 0; i < 4; ++i) v[q][i] = *(const float4*)(xr + i * 256 + lane * 4); }
; __global__ void __launch_bounds__(NTHREADS, 2) megak(Params p) {
;     ...
;                 if (L == 0) for (int t = blockIdx.x; t < 32; t += gridDim.x)
;                     tok0_gemv(lds, T0BR, 1024, nullptr, p.w_out, 1024, T0X1, 1024, p.x, (size_t)SEQ * 1024, t, tid, wid, lane);
.LBB0_514:
	s_nop 0
	s_nop 0
	s_nop 0
	s_nop 0
	s_nop 0
	s_nop 0
	s_nop 0
	s_nop 0
	s_nop 0
	s_nop 0
	s_nop 0
	s_nop 0
	s_nop 0
	s_nop 0
	v_readlane_b32 s14, v252, 14
	v_readlane_b32 s22, v255, 7
	v_readlane_b32 s15, v252, 15
	v_readlane_b32 s23, v255, 8
	s_or_b64 s[14:15], s[22:23], s[14:15]
	s_and_b64 vcc, exec, s[14:15]
	s_cbranch_vccnz .LBB0_652
	v_readlane_b32 s14, v251, 27
	s_waitcnt vmcnt(0)
	v_lshlrev_b32_e32 v8, 4, v238
	v_mov_b32_e32 v9, v12
	v_readlane_b32 s15, v251, 28
	s_ashr_i32 s17, s16, 31
	v_lshrrev_b32_e32 v18, 5, v238
	v_lshl_add_u64 v[0:1], s[14:15], 0, v[8:9]
	s_lshl_b64 s[14:15], s[16:17], 12
	v_lshl_add_u64 v[0:1], v[0:1], 0, s[14:15]
	s_mov_b64 s[14:15], 0x8000
	v_lshl_add_u64 v[2:3], v[0:1], 0, s[14:15]
	s_mov_b64 s[14:15], 0x10000
	v_lshl_add_u64 v[4:5], v[0:1], 0, s[14:15]
	s_lshl_b32 s15, s16, 7
	v_lshl_or_b32 v14, v18, 2, s15
	v_or_b32_e32 v16, 2, v14
	v_ashrrev_i32_e32 v17, 31, v16
	v_lshlrev_b64 v[30:31], 12, v[16:17]
	v_or_b32_e32 v16, 3, v14
	v_ashrrev_i32_e32 v17, 31, v16
	v_lshlrev_b64 v[34:35], 12, v[16:17]
	v_or_b32_e32 v16, 8, v14
	v_ashrrev_i32_e32 v17, 31, v16
	v_lshlrev_b64 v[36:37], 12, v[16:17]
	v_or_b32_e32 v16, 9, v14
	v_ashrrev_i32_e32 v17, 31, v16
	s_waitcnt lgkmcnt(0)
; DI void tok0_gemv(ldsp lds, const float* src, size_t sstride, const float* nw, const float* W, int N, float* Y, int ldy, const float* resid, size_t rstride, int task, int tid, int wid, int lane) {
;     ...
;     const int c0 = task * 32, l31 = lane & 31, kk = lane >> 5, col = c0 + l31; const bool cv = col < N;
;     const int kb = wid * 128;
;     float wv[64];
; #pragma unroll
;     for (int q = 0; q < 16; ++q)
; #pragma unroll
;         for (int e = 0; e < 4; ++e) wv[q * 4 + e] = cv ? W[(size_t)(kb + 8 * q + 4 * kk + e) * N + col] : 0.f;
	v_lshlrev_b64 v[38:39], 12, v[16:17]
	v_or_b32_e32 v16, 10, v14
	v_ashrrev_i32_e32 v17, 31, v16
	v_lshlrev_b64 v[40:41], 12, v[16:17]
	v_or_b32_e32 v16, 11, v14
	v_ashrrev_i32_e32 v17, 31, v16
	v_lshlrev_b64 v[42:43], 12, v[16:17]
	v_or_b32_e32 v16, 16, v14
	v_ashrrev_i32_e32 v17, 31, v16
	v_lshlrev_b64 v[44:45], 12, v[16:17]
	v_or_b32_e32 v16, 17, v14
	v_ashrrev_i32_e32 v17, 31, v16
	v_lshlrev_b64 v[46:47], 12, v[16:17]
	v_or_b32_e32 v16, 18, v14
	v_ashrrev_i32_e32 v17, 31, v16
	v_lshlrev_b64 v[48:49], 12, v[16:17]
	v_or_b32_e32 v16, 19, v14
	v_ashrrev_i32_e32 v17, 31, v16
	v_lshlrev_b64 v[50:51], 12, v[16:17]
	v_or_b32_e32 v16, 24, v14
	v_ashrrev_i32_e32 v17, 31, v16
	v_lshlrev_b64 v[52:53], 12, v[16:17]
	v_or_b32_e32 v16, 25, v14
	v_ashrrev_i32_e32 v17, 31, v16
	v_lshlrev_b64 v[54:55], 12, v[16:17]
	v_or_b32_e32 v16, 26, v14
	v_ashrrev_i32_e32 v17, 31, v16
	v_lshlrev_b64 v[56:57], 12, v[16:17]
	v_or_b32_e32 v16, 27, v14
	v_ashrrev_i32_e32 v17, 31, v16
	v_lshlrev_b64 v[58:59], 12, v[16:17]
	v_or_b32_e32 v16, 32, v14
	v_ashrrev_i32_e32 v17, 31, v16
	v_lshlrev_b64 v[60:61], 12, v[16:17]
	v_or_b32_e32 v16, 33, v14
	v_ashrrev_i32_e32 v17, 31, v16
	v_lshlrev_b64 v[62:63], 12, v[16:17]
	v_or_b32_e32 v16, 34, v14
	v_ashrrev_i32_e32 v17, 31, v16
	v_lshlrev_b64 v[64:65], 12, v[16:17]
	v_or_b32_e32 v16, 35, v14
	v_ashrrev_i32_e32 v17, 31, v16
	v_lshlrev_b64 v[66:67], 12, v[16:17]
	v_or_b32_e32 v16, 40, v14
	v_ashrrev_i32_e32 v17, 31, v16
	v_lshlrev_b64 v[68:69], 12, v[16:17]
	v_or_b32_e32 v16, 41, v14
	v_ashrrev_i32_e32 v17, 31, v16
	v_lshlrev_b64 v[70:71], 12, v[16:17]
	v_or_b32_e32 v16, 42, v14
	v_ashrrev_i32_e32 v17, 31, v16
	v_lshlrev_b64 v[72:73], 12, v[16:17]
	v_or_b32_e32 v16, 43, v14
	v_ashrrev_i32_e32 v17, 31, v16
	v_lshlrev_b64 v[74:75], 12, v[16:17]
	v_or_b32_e32 v16, 48, v14
	v_ashrrev_i32_e32 v17, 31, v16
	v_lshlrev_b64 v[76:77], 12, v[16:17]
	v_or_b32_e32 v16, 49, v14
	v_ashrrev_i32_e32 v17, 31, v16
	v_lshlrev_b64 v[78:79], 12, v[16:17]
	v_or_b32_e32 v16, 50, v14
	v_ashrrev_i32_e32 v17, 31, v16
	v_lshlrev_b64 v[80:81], 12, v[16:17]
	v_or_b32_e32 v16, 51, v14
	v_ashrrev_i32_e32 v17, 31, v16
	v_lshlrev_b64 v[82:83], 12, v[16:17]
	v_or_b32_e32 v16, 56, v14
	v_ashrrev_i32_e32 v17, 31, v16
	v_lshlrev_b64 v[84:85], 12, v[16:17]
	v_or_b32_e32 v16, 57, v14
	v_ashrrev_i32_e32 v17, 31, v16
	v_lshlrev_b64 v[86:87], 12, v[16:17]
	v_or_b32_e32 v16, 58, v14
	v_ashrrev_i32_e32 v17, 31, v16
	v_lshlrev_b64 v[88:89], 12, v[16:17]
	v_or_b32_e32 v16, 59, v14
	v_ashrrev_i32_e32 v17, 31, v16
	v_lshlrev_b64 v[90:91], 12, v[16:17]
	v_or_b32_e32 v16, 64, v14
	v_ashrrev_i32_e32 v17, 31, v16
	v_lshlrev_b64 v[92:93], 12, v[16:17]
	v_or_b32_e32 v16, 0x41, v14
	v_ashrrev_i32_e32 v17, 31, v16
	v_lshlrev_b64 v[94:95], 12, v[16:17]
	v_or_b32_e32 v16, 0x42, v14
	v_ashrrev_i32_e32 v17, 31, v16
	v_lshlrev_b64 v[96:97], 12, v[16:17]
	v_or_b32_e32 v16, 0x43, v14
	v_ashrrev_i32_e32 v17, 31, v16
	v_lshlrev_b64 v[98:99], 12, v[16:17]
	v_or_b32_e32 v16, 0x48, v14
	v_ashrrev_i32_e32 v17, 31, v16
	v_lshlrev_b64 v[100:101], 12, v[16:17]
	v_or_b32_e32 v16, 0x49, v14
	v_ashrrev_i32_e32 v17, 31, v16
	v_lshlrev_b64 v[102:103], 12, v[16:17]
	v_or_b32_e32 v16, 0x4a, v14
	v_ashrrev_i32_e32 v17, 31, v16
	v_lshlrev_b64 v[104:105], 12, v[16:17]
	v_or_b32_e32 v16, 0x4b, v14
	v_ashrrev_i32_e32 v17, 31, v16
	v_lshlrev_b64 v[106:107], 12, v[16:17]
	v_or_b32_e32 v16, 0x50, v14
	v_ashrrev_i32_e32 v17, 31, v16
	v_lshlrev_b64 v[108:109], 12, v[16:17]
	v_or_b32_e32 v16, 0x51, v14
	v_ashrrev_i32_e32 v17, 31, v16
	v_lshlrev_b64 v[110:111], 12, v[16:17]
	v_or_b32_e32 v16, 0x52, v14
	v_ashrrev_i32_e32 v17, 31, v16
	v_lshlrev_b64 v[112:113], 12, v[16:17]
	v_or_b32_e32 v16, 0x53, v14
	v_ashrrev_i32_e32 v17, 31, v16
	v_lshlrev_b64 v[114:115], 12, v[16:17]
	v_or_b32_e32 v16, 0x58, v14
	v_ashrrev_i32_e32 v17, 31, v16
	v_lshlrev_b64 v[116:117], 12, v[16:17]
	v_or_b32_e32 v16, 0x59, v14
	v_ashrrev_i32_e32 v17, 31, v16
	v_lshlrev_b64 v[118:119], 12, v[16:17]
	v_or_b32_e32 v16, 0x5a, v14
	v_ashrrev_i32_e32 v17, 31, v16
	v_lshlrev_b64 v[120:121], 12, v[16:17]
	v_or_b32_e32 v16, 0x5b, v14
	v_ashrrev_i32_e32 v17, 31, v16
	v_lshlrev_b64 v[122:123], 12, v[16:17]
	v_or_b32_e32 v16, 0x60, v14
	v_ashrrev_i32_e32 v17, 31, v16
	v_lshlrev_b64 v[124:125], 12, v[16:17]
	v_or_b32_e32 v16, 0x61, v14
	v_ashrrev_i32_e32 v17, 31, v16
	v_lshlrev_b64 v[126:127], 12, v[16:17]
	v_or_b32_e32 v16, 0x62, v14
	v_ashrrev_i32_e32 v17, 31, v16
	v_lshlrev_b64 v[128:129], 12, v[16:17]
	v_or_b32_e32 v16, 0x63, v14
	v_ashrrev_i32_e32 v17, 31, v16
	v_lshlrev_b64 v[130:131], 12, v[16:17]
	v_or_b32_e32 v16, 0x68, v14
	v_ashrrev_i32_e32 v17, 31, v16
	v_lshlrev_b64 v[132:133], 12, v[16:17]
	v_or_b32_e32 v16, 0x69, v14
	v_ashrrev_i32_e32 v17, 31, v16
	v_lshlrev_b64 v[134:135], 12, v[16:17]
	v_or_b32_e32 v16, 0x6a, v14
	v_ashrrev_i32_e32 v17, 31, v16
	v_lshlrev_b64 v[136:137], 12, v[16:17]
	v_or_b32_e32 v16, 0x6b, v14
	v_ashrrev_i32_e32 v17, 31, v16
	v_lshlrev_b64 v[138:139], 12, v[16:17]
	v_or_b32_e32 v16, 0x70, v14
	v_ashrrev_i32_e32 v17, 31, v16
	v_lshlrev_b64 v[140:141], 12, v[16:17]
	v_or_b32_e32 v16, 0x71, v14
	v_ashrrev_i32_e32 v17, 31, v16
	v_lshlrev_b64 v[142:143], 12, v[16:17]
	v_or_b32_e32 v16, 0x72, v14
	v_ashrrev_i32_e32 v17, 31, v16
	v_lshlrev_b64 v[144:145], 12, v[16:17]
	v_or_b32_e32 v16, 0x73, v14
	v_ashrrev_i32_e32 v17, 31, v16
	v_lshlrev_b64 v[146:147], 12, v[16:17]
	v_or_b32_e32 v16, 0x78, v14
	v_ashrrev_i32_e32 v17, 31, v16
	v_lshlrev_b64 v[148:149], 12, v[16:17]
	v_or_b32_e32 v16, 0x79, v14
	v_ashrrev_i32_e32 v15, 31, v14
	v_ashrrev_i32_e32 v17, 31, v16
	v_add_u32_e32 v13, 0, v8
	v_lshlrev_b64 v[8:9], 12, v[14:15]
	v_or_b32_e32 v10, 1, v14
	v_lshlrev_b64 v[150:151], 12, v[16:17]
	v_or_b32_e32 v16, 0x7a, v14
	v_or_b32_e32 v14, 0x7b, v14
	v_and_b32_e32 v33, 31, v32
	v_ashrrev_i32_e32 v15, 31, v14
	s_movk_i32 s15, 0x1010
	v_ashrrev_i32_e32 v17, 31, v16
	v_lshlrev_b64 v[162:163], 12, v[14:15]
	v_mad_u32_u24 v14, v33, s15, 0
	s_lshl_b32 s15, s16, 12
	v_lshlrev_b64 v[152:153], 12, v[16:17]
	v_lshlrev_b32_e32 v16, 4, v18
	s_add_i32 s15, s15, 0
	v_lshlrev_b32_e32 v17, 9, v18
	v_lshlrev_b32_e32 v18, 2, v33
	v_add3_u32 v155, s15, v17, v18
	s_movk_i32 s15, 0x400
	s_mul_i32 s0, s16, 0x1010
	v_ashrrev_i32_e32 v11, 31, v10
	v_lshl_add_u32 v15, s16, 9, v14
	v_cmp_gt_i32_e64 s[38:39], s15, v32
	s_movk_i32 s15, 0xeff4
	v_lshl_add_u64 v[6:7], v[0:1], 0, s[28:29]
	s_add_i32 s14, s0, 0x10100
	v_lshlrev_b64 v[10:11], 12, v[10:11]
	v_mad_i32_i24 v156, v33, s15, v14
	v_add_u32_e32 v166, v15, v16
	s_mov_b32 s15, s78
	s_branch .LBB0_517
